# combine: only wave 0 polls the partial counter, the other waves wait at a workgroup barrier (8x fewer pollers on each counter line)
# baseline (speedup 1.0000x reference)
.LBB0_209:
	s_cmp_lg_u32 s86, 0
	s_cbranch_scc1 .Lcmb_go
	s_load_dwordx2 s[4:5], s[66:67], 0x100
	v_mov_b32_e32 v0, 0x20178
	ds_read_b32 v18, v0
	v_readlane_b32 s6, v255, 0
	s_nop 3
	s_lshr_b32 s6, s6, 3
	s_lshl_b32 s6, s6, 8
	s_add_u32 s6, s6, 0xe800480
	s_waitcnt lgkmcnt(0)
	s_add_u32 s4, s4, s6
	s_addc_u32 s5, s5, 0

.Lcmb_go:
	s_barrier
	s_cmpk_lt_i32 s26, 0x1000
	s_cselect_b64 s[40:41], -1, 0
	s_add_i32 s44, s26, 0xfffff000
	s_cmpk_gt_i32 s26, 0xfff
	s_mov_b64 s[6:7], -1
	s_cbranch_scc0 .LBB0_211
	s_lshl_b64 s[4:5], s[44:45], 12
	s_add_u32 s42, s24, s4
	s_addc_u32 s43, s25, s5
	s_mov_b32 s4, s26
	s_mov_b32 s5, s45
	s_mov_b64 s[6:7], 0
